# hyena sample path: LDS relayout of the 8 shifted filter copies so the e-loop ds_read_b128 A reads are bank-conflict-free (were 3-way)
# speedup vs baseline: 1.0328x; 1.0211x over previous
.LBB0_563:
	s_and_b64 vcc, exec, s[0:1]
	s_cbranch_vccz .LBB0_466
	v_readlane_b32 s0, v255, 23
	v_lshlrev_b64 v[0:1], 14, v[60:61]
	v_readlane_b32 s1, v255, 24
	v_lshlrev_b32_e32 v20, 4, v60
	v_ashrrev_i32_e32 v2, 8, v60
	v_lshl_add_u64 v[0:1], s[0:1], 0, v[0:1]
	s_mov_b64 s[0:1], 0x40000
	v_lshl_add_u64 v[18:19], v[0:1], 0, s[0:1]
	v_and_b32_e32 v0, 0x1ff, v60
	v_lshlrev_b32_e32 v16, 3, v0
	v_lshlrev_b32_e32 v0, 4, v0
	v_mov_b32_e32 v1, v112
	v_lshl_add_u64 v[0:1], s[8:9], 0, v[0:1]
	s_mov_b64 s[0:1], 0x4004000
	v_lshl_add_u64 v[0:1], v[0:1], 0, s[0:1]
	s_mov_b32 s1, 0x20200
	s_movk_i32 s4, 0xe000
	v_add_u32_e32 v11, 0xffffe002, v20
	v_mov_b32_e32 v6, s1
	v_mad_i32_i24 v7, v2, s74, v6
	v_cmp_lt_u32_e64 s[74:75], s4, v11
	v_or_b32_e32 v11, 3, v20
	v_add_u32_e32 v12, 0xffffe003, v20
	v_cmp_lt_u32_e64 s[76:77], s4, v12
	v_sub_u32_e32 v12, 0x1000, v11
	v_or_b32_e32 v11, 4, v20
	v_sub_u32_e32 v14, 0x1000, v11
	v_or_b32_e32 v11, 5, v20
	v_sub_u32_e32 v84, 0x1000, v11
	v_or_b32_e32 v11, 6, v20
	v_sub_u32_e32 v86, 0x1000, v11
	v_or_b32_e32 v11, 7, v20
	v_sub_u32_e32 v88, 0x1000, v11
	v_or_b32_e32 v11, 8, v20
	v_sub_u32_e32 v90, 0x1000, v11
	v_or_b32_e32 v11, 9, v20
	v_sub_u32_e32 v92, 0x1000, v11
	v_or_b32_e32 v11, 10, v20
	v_sub_u32_e32 v94, 0x1000, v11
	v_or_b32_e32 v11, 11, v20
	v_bfe_u32 v4, v60, 3, 6
	v_sub_u32_e32 v96, 0x1000, v11
	v_or_b32_e32 v11, 12, v20
	v_mul_u32_u24_e32 v4, 0x90, v4
	v_and_b32_e32 v5, 0x70, v20
	v_sub_u32_e32 v98, 0x1000, v11
	v_or_b32_e32 v11, 13, v20
	v_add3_u32 v17, s1, v4, v5
	s_movk_i32 s1, 0xfff
	v_sub_u32_e32 v100, 0x1000, v11
	v_or_b32_e32 v11, 14, v20
	v_add_u32_e32 v24, 16, v20
	v_sub_u32_e32 v102, 0x1000, v11
	v_or_b32_e32 v11, 15, v20
	v_cmp_lt_u32_e64 s[12:13], s1, v24
	s_movk_i32 s5, 0x1000
	v_sub_u32_e32 v104, 0x1000, v11
	v_add_u32_e32 v11, 0xffffe010, v20
	v_writelane_b32 v255, s12, 7
	v_cmp_lt_u32_e64 s[46:47], s4, v11
	v_add_u32_e32 v11, 0xffffe011, v20
	v_writelane_b32 v255, s13, 8
	v_cmp_ne_u32_e64 s[12:13], s5, v24
	v_add_u32_e32 v28, 17, v20
	v_cmp_lt_u32_e64 s[52:53], s4, v11
	v_writelane_b32 v255, s12, 28
	v_add_u32_e32 v11, 0xffffe012, v20
	v_cmp_lt_u32_e64 s[56:57], s4, v11
	v_writelane_b32 v255, s13, 29
	v_cmp_lt_u32_e64 s[12:13], s1, v28
	v_add_u32_e32 v11, 0xffffe013, v20
	v_add_u32_e32 v13, 0xffffe004, v20
	v_writelane_b32 v255, s12, 11
	v_add_u32_e32 v32, 18, v20
	v_cmp_lt_u32_e64 s[60:61], s4, v11
	v_add_u32_e32 v11, 0xffffe014, v20
	v_cmp_gt_u32_e64 s[14:15], s64, v20
	v_cmp_lt_u32_e64 s[78:79], s4, v13
	v_add_u32_e32 v13, 0xffffe005, v20
	v_writelane_b32 v255, s13, 12
	v_cmp_lt_u32_e64 s[12:13], s1, v32
	v_cmp_lt_u32_e64 s[64:65], s4, v11
	v_add_u32_e32 v11, 0xffffe015, v20
	v_cmp_lt_u32_e64 s[86:87], s4, v13
	v_add_u32_e32 v13, 0xffffe006, v20
	v_writelane_b32 v255, s12, 9
	v_add_u32_e32 v36, 19, v20
	v_cmp_lt_u32_e64 s[68:69], s4, v11
	v_add_u32_e32 v11, 0xffffe016, v20
	v_cmp_lt_u32_e64 s[58:59], s4, v13
	v_add_u32_e32 v13, 0xffffe007, v20
	v_writelane_b32 v255, s13, 10
	v_cmp_lt_u32_e64 s[12:13], s1, v36
	v_cmp_lt_u32_e64 s[72:73], s4, v11
	v_ashrrev_i32_e32 v11, 9, v60
	v_cmp_lt_u32_e64 s[62:63], s4, v13
	v_add_u32_e32 v13, 0xffffe008, v20
	v_writelane_b32 v255, s12, 13
	v_add_u32_e32 v40, 20, v20
	v_lshlrev_b32_e32 v50, 12, v11
	v_mul_i32_i24_e32 v67, 0x2400, v11
	v_ashrrev_i32_e32 v11, 9, v58
	v_and_b32_e32 v4, 32, v65
	v_lshrrev_b32_e32 v6, 2, v60
	v_cmp_lt_u32_e64 s[66:67], s4, v13
	v_add_u32_e32 v13, 0xffffe009, v20
	v_writelane_b32 v255, s13, 14
	v_cmp_lt_u32_e64 s[12:13], s1, v40
	v_lshlrev_b32_e32 v42, 12, v11
	v_and_or_b32 v6, v6, 32, v62
	v_lshlrev_b32_e32 v22, 12, v2
	v_lshl_or_b32 v2, v59, 2, v4
	v_cmp_lt_u32_e64 s[70:71], s4, v13
	v_add_u32_e32 v13, 0xffffe00a, v20
	v_writelane_b32 v255, s12, 30
	v_add_u32_e32 v46, 21, v20
	v_add_u32_e32 v52, 22, v20
	v_ashrrev_i32_e32 v51, 31, v50
	v_ashrrev_i32_e32 v43, 31, v42
	v_and_b32_e32 v5, 7, v66
	v_mul_u32_u24_e32 v9, 0x90, v6
	v_cmp_lt_u32_e64 s[10:11], s1, v20
	v_cmp_lt_u32_e64 s[34:35], s4, v13
	v_add_u32_e32 v13, 0xffffe00b, v20
	v_writelane_b32 v255, s13, 31
	v_cmp_lt_u32_e64 s[12:13], s1, v46
	v_cmp_lt_u32_e64 s[84:85], s1, v52
	v_lshl_add_u64 v[56:57], v[50:51], 1, v[0:1]
	v_lshl_add_u64 v[58:59], v[42:43], 1, v[0:1]
	v_lshlrev_b32_e32 v0, 1, v2
	s_movk_i32 s1, 0x4010
	v_cmp_lt_u32_e64 s[36:37], s4, v13
	v_add_u32_e32 v13, 0xffffe00c, v20
	v_add3_u32 v76, v7, v9, v0
	v_mad_u32_u24 v0, v5, s1, v63
	v_add_lshl_u32 v1, v5, v62, 1
	s_mov_b32 s2, 0
	v_lshlrev_b32_e32 v3, 5, v60
	v_cmp_lt_u32_e64 s[38:39], s4, v13
	v_add_u32_e32 v13, 0xffffe00d, v20
	v_sub_u32_e32 v0, v0, v1
	v_and_b32_e32 v1, 64, v60
	s_movk_i32 s3, 0x5eed
	v_lshlrev_b32_e32 v4, 6, v6
	v_add_u32_e32 v6, 0xffffe000, v20
	v_or_b32_e32 v8, 1, v20
	v_or_b32_e32 v10, 2, v20
	v_cmp_lt_u32_e64 s[40:41], s4, v13
	v_add_u32_e32 v13, 0xffffe00e, v20
	v_sub_u32_e32 v0, v0, v1
	v_and_b32_e32 v1, 0x1000, v3
	s_movk_i32 s3, 0x100
	v_add_u32_e32 v64, 0, v3
	v_cmp_lt_u32_e64 s[8:9], s4, v6
	v_sub_u32_e32 v6, 0x1000, v20
	v_sub_u32_e32 v8, 0x1000, v8
	v_sub_u32_e32 v10, 0x1000, v10
	v_cmp_lt_u32_e64 s[42:43], s4, v13
	v_add_u32_e32 v13, 0xffffe00f, v20
	v_writelane_b32 v255, s12, 32
	v_sub_u32_e32 v0, v0, v1
	v_cmp_gt_i32_e64 s[6:7], s3, v60
	s_mov_b32 s0, 0
	v_add_u32_e32 v65, v7, v63
	s_or_b32 s82, s90, 0x1000000
	v_ashrrev_i32_e32 v23, 31, v22
	v_cmp_ne_u32_e64 s[96:97], s3, v60
	v_mov_b32_e32 v21, v112
	v_cmp_lt_u32_e64 s[44:45], s4, v13
	v_mov_b32_e32 v25, v112
	v_sub_u32_e32 v26, 0xff0, v20
	v_mov_b32_e32 v27, v112
	v_mov_b32_e32 v29, v112
	v_sub_u32_e32 v30, 0xfef, v20
	v_mov_b32_e32 v31, v112
	v_mov_b32_e32 v33, v112
	v_sub_u32_e32 v34, 0xfee, v20
	v_mov_b32_e32 v35, v112
	v_mov_b32_e32 v37, v112
	v_sub_u32_e32 v38, 0xfed, v20
	v_mov_b32_e32 v39, v112
	v_mov_b32_e32 v41, v112
	v_sub_u32_e32 v44, 0xfec, v20
	v_mov_b32_e32 v45, v112
	v_writelane_b32 v255, s13, 33
	v_mov_b32_e32 v47, v112
	v_sub_u32_e32 v48, 0xfeb, v20
	v_mov_b32_e32 v49, v112
	v_mov_b32_e32 v53, v112
	v_sub_u32_e32 v54, 0xfea, v20
	v_mov_b32_e32 v55, v112
	v_add_u32_e32 v68, 0x10040, v64
	v_add_u32_e32 v69, 0x10050, v64
	v_add_u32_e32 v70, 0x14050, v64
	v_add_u32_e32 v71, 0x14060, v64
	v_add_u32_e32 v72, 0x18060, v64
	v_add_u32_e32 v73, 0x18070, v64
	v_add_u32_e32 v74, 0x1c070, v64
	v_add_u32_e32 v75, 0x1c080, v64
	v_mul_i32_i24_e32 v66, 0x2400, v11
	v_add_u32_e32 v77, 0, v0
	v_sub_u32_e32 v126, 0, v192
	v_and_b32_e32 v126, 7, v126
	v_add_u32_e32 v127, -1, v126
	v_mul_i32_i24_e32 v127, 3, v127
	v_max_i32_e32 v127, 0, v127
	v_cmp_lt_u32_e64 s[88:89], 4, v126
	s_nop 1
	v_cndmask_b32_e64 v126, 0, 4, s[88:89]
	v_add_u32_e32 v127, v127, v126
	v_lshl_add_u32 v77, v127, 4, v77
	v_add_u32_e32 v78, 63, v62
	s_mov_b64 s[88:89], -1
	v_lshlrev_b32_e32 v79, 2, v6
	v_lshlrev_b32_e32 v80, 2, v8
	v_lshlrev_b32_e32 v81, 2, v10
	v_lshlrev_b32_e32 v82, 2, v12
	v_lshlrev_b32_e32 v83, 2, v14
	v_lshlrev_b32_e32 v84, 2, v84
	v_lshlrev_b32_e32 v85, 2, v86
	v_lshlrev_b32_e32 v86, 2, v88
	v_lshlrev_b32_e32 v87, 2, v90
	v_lshlrev_b32_e32 v88, 2, v92
	v_lshlrev_b32_e32 v89, 2, v94
	v_lshlrev_b32_e32 v90, 2, v96
	v_lshlrev_b32_e32 v91, 2, v98
	v_lshlrev_b32_e32 v92, 2, v100
	v_lshlrev_b32_e32 v93, 2, v102
	v_lshlrev_b32_e32 v94, 2, v104
	v_lshlrev_b32_e32 v60, 1, v4
	v_lshlrev_b32_e32 v62, 1, v2
	s_movk_i32 s83, 0x90

.LBB0_567:
	s_or_b64 exec, exec, s[0:1]
	v_mov_b32_e32 v1, v192
	v_mov_b32_e32 v2, v192
	v_lshlrev_b32_e32 v1, 2, v1
	v_bitop3_b32 v1, v1, s33, v203 bitop3:0x6c
	s_waitcnt vmcnt(0)
	ds_bpermute_b32 v1, v1, v0
	s_waitcnt lgkmcnt(0)
	v_add_f32_e32 v0, v0, v1
	v_lshlrev_b32_e32 v2, 2, v2
	v_bitop3_b32 v2, v2, 64, v203 bitop3:0x6c
	ds_bpermute_b32 v1, v2, v0
	v_mov_b32_e32 v2, v192
	s_waitcnt lgkmcnt(0)
	v_add_f32_e32 v0, v0, v1
	v_lshlrev_b32_e32 v2, 2, v2
	v_bitop3_b32 v2, v2, 32, v203 bitop3:0x6c
	ds_bpermute_b32 v1, v2, v0
	v_mov_b32_e32 v2, v192
	s_waitcnt lgkmcnt(0)
	v_add_f32_e32 v0, v0, v1
	v_lshlrev_b32_e32 v2, 2, v2
	v_bitop3_b32 v2, v2, 16, v203 bitop3:0x6c
	ds_bpermute_b32 v1, v2, v0
	v_mov_b32_e32 v2, v192
	s_waitcnt lgkmcnt(0)
	v_add_f32_e32 v0, v0, v1
	v_lshlrev_b32_e32 v2, 2, v2
	v_bitop3_b32 v2, v2, 8, v203 bitop3:0x6c
	ds_bpermute_b32 v1, v2, v0
	v_mov_b32_e32 v2, v192
	s_waitcnt lgkmcnt(0)
	v_add_f32_e32 v0, v0, v1
	v_lshlrev_b32_e32 v2, 2, v2
	v_bitop3_b32 v1, v2, 4, v203 bitop3:0x6c
	ds_bpermute_b32 v1, v1, v0
	v_mov_b32_e32 v2, v192
	s_nop 0
	v_and_b32_e32 v2, 63, v2
	v_cmp_eq_u32_e32 vcc, 0, v2
	s_and_saveexec_b64 s[0:1], vcc
	s_cbranch_execz .LBB0_569
	s_waitcnt lgkmcnt(0)
	v_add_f32_e32 v0, v0, v1
	v_mov_b32_e32 v1, v192
	s_nop 0
	v_ashrrev_i32_e32 v1, 6, v1
	v_lshl_add_u32 v1, v1, 2, 0
	v_add_u32_e32 v1, 0x24a80, v1
	ds_write_b32 v1, v0

.LBB0_571:
	s_or_b64 exec, exec, s[0:1]
	s_waitcnt lgkmcnt(0)
	v_mov_b32_e32 v1, v192
	v_mov_b32_e32 v2, v192
	v_lshlrev_b32_e32 v1, 2, v1
	v_bitop3_b32 v1, v1, s33, v203 bitop3:0x6c
	s_waitcnt vmcnt(0)
	ds_bpermute_b32 v1, v1, v0
	s_waitcnt lgkmcnt(0)
	v_add_f32_e32 v0, v0, v1
	v_lshlrev_b32_e32 v2, 2, v2
	v_bitop3_b32 v2, v2, 64, v203 bitop3:0x6c
	ds_bpermute_b32 v1, v2, v0
	v_mov_b32_e32 v2, v192
	s_waitcnt lgkmcnt(0)
	v_add_f32_e32 v0, v0, v1
	v_lshlrev_b32_e32 v2, 2, v2
	v_bitop3_b32 v2, v2, 32, v203 bitop3:0x6c
	ds_bpermute_b32 v1, v2, v0
	v_mov_b32_e32 v2, v192
	s_waitcnt lgkmcnt(0)
	v_add_f32_e32 v0, v0, v1
	v_lshlrev_b32_e32 v2, 2, v2
	v_bitop3_b32 v2, v2, 16, v203 bitop3:0x6c
	ds_bpermute_b32 v1, v2, v0
	v_mov_b32_e32 v2, v192
	s_waitcnt lgkmcnt(0)
	v_add_f32_e32 v0, v0, v1
	v_lshlrev_b32_e32 v2, 2, v2
	v_bitop3_b32 v2, v2, 8, v203 bitop3:0x6c
	ds_bpermute_b32 v1, v2, v0
	v_mov_b32_e32 v2, v192
	s_waitcnt lgkmcnt(0)
	v_add_f32_e32 v0, v0, v1
	v_lshlrev_b32_e32 v2, 2, v2
	v_bitop3_b32 v1, v2, 4, v203 bitop3:0x6c
	ds_bpermute_b32 v1, v1, v0
	v_mov_b32_e32 v2, v192
	s_nop 0
	v_and_b32_e32 v2, 63, v2
	v_cmp_eq_u32_e32 vcc, 0, v2
	s_and_saveexec_b64 s[0:1], vcc
	s_cbranch_execz .LBB0_573
	s_waitcnt lgkmcnt(0)
	v_add_f32_e32 v0, v0, v1
	v_mov_b32_e32 v1, v192
	s_nop 0
	v_ashrrev_i32_e32 v1, 6, v1
	v_lshl_add_u32 v1, v1, 2, 0
	v_add_u32_e32 v1, 0x24aa0, v1
	ds_write_b32 v1, v0
.LBB0_573:
	s_or_b64 exec, exec, s[0:1]
	s_add_i32 s0, 0, 0x24a80
	v_mov_b32_e32 v12, s0
	s_waitcnt lgkmcnt(0)
	s_barrier
	ds_read_b128 v[0:3], v12
	ds_read_b128 v[4:7], v12 offset:16
	ds_read_b128 v[8:11], v12 offset:32
	ds_read_b128 v[12:15], v12 offset:48
	s_mov_b32 s0, 0x358637bd
	s_waitcnt lgkmcnt(3)
	v_mov_b32_e32 v96, v0
	s_mov_b32 s4, 0
	s_waitcnt lgkmcnt(1)
	v_mov_b32_e32 v97, v8
	v_pk_add_f32 v[96:97], v[96:97], 0 op_sel_hi:[1,0]
	v_mov_b32_e32 v8, v1
	v_pk_add_f32 v[0:1], v[96:97], v[8:9]
	v_mov_b32_e32 v8, v2
	v_mov_b32_e32 v9, v10
	v_pk_add_f32 v[0:1], v[0:1], v[8:9]
	v_mov_b32_e32 v10, v3
	v_pk_add_f32 v[0:1], v[0:1], v[10:11]
	v_mov_b32_e32 v2, v4
	s_waitcnt lgkmcnt(0)
	v_mov_b32_e32 v3, v12
	v_pk_add_f32 v[0:1], v[0:1], v[2:3]
	v_mov_b32_e32 v12, v5
	v_pk_add_f32 v[0:1], v[0:1], v[12:13]
	v_mov_b32_e32 v2, v6
	v_mov_b32_e32 v3, v14
	v_pk_add_f32 v[0:1], v[0:1], v[2:3]
	v_mov_b32_e32 v14, v7
	v_pk_add_f32 v[0:1], v[0:1], v[14:15]
	s_movk_i32 s5, 0x5eed
	v_pk_add_f32 v[0:1], v[0:1], s[0:1] op_sel_hi:[1,0]
	s_mov_b32 s13, s4
	v_div_scale_f32 v2, s[0:1], v1, v1, 1.0
	v_rcp_f32_e32 v3, v2
	v_readlane_b32 s16, v254, 10
	v_readlane_b32 s22, v254, 16
	v_readlane_b32 s23, v254, 17
	v_fma_f32 v4, -v2, v3, 1.0
	v_fmac_f32_e32 v3, v4, v3
	v_div_scale_f32 v4, vcc, 1.0, v1, 1.0
	v_mul_f32_e32 v5, v4, v3
	v_fma_f32 v6, -v2, v5, v4
	v_fmac_f32_e32 v5, v6, v3
	v_fma_f32 v2, -v2, v5, v4
	v_div_fmas_f32 v2, v2, v3, v5
	v_div_fixup_f32 v1, v2, v1, 1.0
	v_div_scale_f32 v2, s[0:1], v0, v0, 1.0
	v_rcp_f32_e32 v3, v2
	s_lshl_b64 s[0:1], s[12:13], 2
	s_add_u32 s0, s22, s0
	s_addc_u32 s1, s23, s1
	v_fma_f32 v4, -v2, v3, 1.0
	v_fmac_f32_e32 v3, v4, v3
	v_div_scale_f32 v4, vcc, 1.0, v0, 1.0
	v_mul_f32_e32 v5, v4, v3
	v_fma_f32 v6, -v2, v5, v4
	v_fmac_f32_e32 v5, v6, v3
	v_fma_f32 v2, -v2, v5, v4
	global_load_dword v4, v112, s[0:1]
	s_lshl_b64 s[0:1], s[12:13], 14
	s_add_u32 s80, s91, s0
	s_addc_u32 s81, s54, s1
	s_lshl_b32 s0, s50, 12
	s_mov_b32 s1, s4
	s_lshl_b64 s[0:1], s[0:1], 2
	v_div_fmas_f32 v2, v2, v3, v5
	s_add_u32 s12, s91, s0
	v_div_fixup_f32 v0, v2, v0, 1.0
	s_mov_b32 s2, 0
	s_addc_u32 s13, s54, s1
	v_mov_b32_e32 v2, 0
	v_mov_b32_e32 v3, 0
	v_readlane_b32 s17, v254, 11
	v_readlane_b32 s18, v254, 12
	v_readlane_b32 s19, v254, 13
	v_readlane_b32 s20, v254, 14
	v_readlane_b32 s21, v254, 15
	v_readlane_b32 s24, v254, 18
	v_readlane_b32 s25, v254, 19
	v_readlane_b32 s26, v254, 20
	v_readlane_b32 s27, v254, 21
	v_readlane_b32 s28, v254, 22
	v_readlane_b32 s29, v254, 23
	v_readlane_b32 s30, v254, 24
	v_readlane_b32 s31, v254, 25
	s_movk_i32 s3, 0x5eed
	s_sub_u32 s0, s12, s80
	v_lshlrev_b32_e32 v248, 4, v192
	v_sub_u32_e32 v213, 0x1000, v248
	v_sub_u32_e32 v249, 0, v213
	v_max_i32_e32 v249, v213, v249
	v_ashrrev_i32_e32 v250, 31, v213
	v_and_b32_e32 v250, s0, v250
	v_lshl_add_u32 v249, v249, 2, v250
	global_load_dword v95, v249, s[80:81]
	v_add_u32_e32 v214, -1, v213
	v_sub_u32_e32 v249, 0, v214
	v_max_i32_e32 v249, v214, v249
	v_ashrrev_i32_e32 v250, 31, v214
	v_and_b32_e32 v250, s0, v250
	v_lshl_add_u32 v249, v249, 2, v250
	global_load_dword v96, v249, s[80:81]
	v_add_u32_e32 v215, -2, v213
	v_sub_u32_e32 v249, 0, v215
	v_max_i32_e32 v249, v215, v249
	v_ashrrev_i32_e32 v250, 31, v215
	v_and_b32_e32 v250, s0, v250
	v_lshl_add_u32 v249, v249, 2, v250
	global_load_dword v97, v249, s[80:81]
	v_add_u32_e32 v216, -3, v213
	v_sub_u32_e32 v249, 0, v216
	v_max_i32_e32 v249, v216, v249
	v_ashrrev_i32_e32 v250, 31, v216
	v_and_b32_e32 v250, s0, v250
	v_lshl_add_u32 v249, v249, 2, v250
	global_load_dword v98, v249, s[80:81]
	v_add_u32_e32 v217, -4, v213
	v_sub_u32_e32 v249, 0, v217
	v_max_i32_e32 v249, v217, v249
	v_ashrrev_i32_e32 v250, 31, v217
	v_and_b32_e32 v250, s0, v250
	v_lshl_add_u32 v249, v249, 2, v250
	global_load_dword v99, v249, s[80:81]
	v_add_u32_e32 v218, -5, v213
	v_sub_u32_e32 v249, 0, v218
	v_max_i32_e32 v249, v218, v249
	v_ashrrev_i32_e32 v250, 31, v218
	v_and_b32_e32 v250, s0, v250
	v_lshl_add_u32 v249, v249, 2, v250
	global_load_dword v100, v249, s[80:81]
	v_add_u32_e32 v219, -6, v213
	v_sub_u32_e32 v249, 0, v219
	v_max_i32_e32 v249, v219, v249
	v_ashrrev_i32_e32 v250, 31, v219
	v_and_b32_e32 v250, s0, v250
	v_lshl_add_u32 v249, v249, 2, v250
	global_load_dword v101, v249, s[80:81]
	v_add_u32_e32 v220, -7, v213
	v_sub_u32_e32 v249, 0, v220
	v_max_i32_e32 v249, v220, v249
	v_ashrrev_i32_e32 v250, 31, v220
	v_and_b32_e32 v250, s0, v250
	v_lshl_add_u32 v249, v249, 2, v250
	global_load_dword v102, v249, s[80:81]
	v_add_u32_e32 v221, -8, v213
	v_sub_u32_e32 v249, 0, v221
	v_max_i32_e32 v249, v221, v249
	v_ashrrev_i32_e32 v250, 31, v221
	v_and_b32_e32 v250, s0, v250
	v_lshl_add_u32 v249, v249, 2, v250
	global_load_dword v103, v249, s[80:81]
	v_add_u32_e32 v222, -9, v213
	v_sub_u32_e32 v249, 0, v222
	v_max_i32_e32 v249, v222, v249
	v_ashrrev_i32_e32 v250, 31, v222
	v_and_b32_e32 v250, s0, v250
	v_lshl_add_u32 v249, v249, 2, v250
	global_load_dword v104, v249, s[80:81]
	v_add_u32_e32 v223, -10, v213
	v_sub_u32_e32 v249, 0, v223
	v_max_i32_e32 v249, v223, v249
	v_ashrrev_i32_e32 v250, 31, v223
	v_and_b32_e32 v250, s0, v250
	v_lshl_add_u32 v249, v249, 2, v250
	global_load_dword v105, v249, s[80:81]
	v_add_u32_e32 v224, -11, v213
	v_sub_u32_e32 v249, 0, v224
	v_max_i32_e32 v249, v224, v249
	v_ashrrev_i32_e32 v250, 31, v224
	v_and_b32_e32 v250, s0, v250
	v_lshl_add_u32 v249, v249, 2, v250
	global_load_dword v106, v249, s[80:81]
	v_add_u32_e32 v225, -12, v213
	v_sub_u32_e32 v249, 0, v225
	v_max_i32_e32 v249, v225, v249
	v_ashrrev_i32_e32 v250, 31, v225
	v_and_b32_e32 v250, s0, v250
	v_lshl_add_u32 v249, v249, 2, v250
	global_load_dword v107, v249, s[80:81]
	v_add_u32_e32 v226, -13, v213
	v_sub_u32_e32 v249, 0, v226
	v_max_i32_e32 v249, v226, v249
	v_ashrrev_i32_e32 v250, 31, v226
	v_and_b32_e32 v250, s0, v250
	v_lshl_add_u32 v249, v249, 2, v250
	global_load_dword v108, v249, s[80:81]
	v_add_u32_e32 v227, -14, v213
	v_sub_u32_e32 v249, 0, v227
	v_max_i32_e32 v249, v227, v249
	v_ashrrev_i32_e32 v250, 31, v227
	v_and_b32_e32 v250, s0, v250
	v_lshl_add_u32 v249, v249, 2, v250
	global_load_dword v109, v249, s[80:81]
	v_add_u32_e32 v228, -15, v213
	v_sub_u32_e32 v249, 0, v228
	v_max_i32_e32 v249, v228, v249
	v_ashrrev_i32_e32 v250, 31, v228
	v_and_b32_e32 v250, s0, v250
	v_lshl_add_u32 v249, v249, 2, v250
	global_load_dword v110, v249, s[80:81]
	v_add_u32_e32 v229, -16, v213
	v_sub_u32_e32 v249, 0, v229
	v_max_i32_e32 v249, v229, v249
	v_ashrrev_i32_e32 v250, 31, v229
	v_and_b32_e32 v250, s0, v250
	v_lshl_add_u32 v249, v249, 2, v250
	global_load_dword v111, v249, s[80:81]
	v_add_u32_e32 v230, -17, v213
	v_sub_u32_e32 v249, 0, v230
	v_max_i32_e32 v249, v230, v249
	v_ashrrev_i32_e32 v250, 31, v230
	v_and_b32_e32 v250, s0, v250
	v_lshl_add_u32 v249, v249, 2, v250
	global_load_dword v122, v249, s[80:81]
	v_add_u32_e32 v231, -18, v213
	v_sub_u32_e32 v249, 0, v231
	v_max_i32_e32 v249, v231, v249
	v_ashrrev_i32_e32 v250, 31, v231
	v_and_b32_e32 v250, s0, v250
	v_lshl_add_u32 v249, v249, 2, v250
	global_load_dword v123, v249, s[80:81]
	v_add_u32_e32 v232, -19, v213
	v_sub_u32_e32 v249, 0, v232
	v_max_i32_e32 v249, v232, v249
	v_ashrrev_i32_e32 v250, 31, v232
	v_and_b32_e32 v250, s0, v250
	v_lshl_add_u32 v249, v249, 2, v250
	global_load_dword v124, v249, s[80:81]
	v_add_u32_e32 v233, -20, v213
	v_sub_u32_e32 v249, 0, v233
	v_max_i32_e32 v249, v233, v249
	v_ashrrev_i32_e32 v250, 31, v233
	v_and_b32_e32 v250, s0, v250
	v_lshl_add_u32 v249, v249, 2, v250
	global_load_dword v125, v249, s[80:81]
	v_add_u32_e32 v234, -21, v213
	v_sub_u32_e32 v249, 0, v234
	v_max_i32_e32 v249, v234, v249
	v_ashrrev_i32_e32 v250, 31, v234
	v_and_b32_e32 v250, s0, v250
	v_lshl_add_u32 v249, v249, 2, v250
	global_load_dword v126, v249, s[80:81]
	v_add_u32_e32 v235, -22, v213
	v_sub_u32_e32 v249, 0, v235
	v_max_i32_e32 v249, v235, v249
	v_ashrrev_i32_e32 v250, 31, v235
	v_and_b32_e32 v250, s0, v250
	v_lshl_add_u32 v249, v249, 2, v250
	global_load_dword v127, v249, s[80:81]
	global_load_dword v246, v112, s[80:81]
	global_load_dword v247, v112, s[12:13]
	v_lshlrev_b32_e32 v251, 5, v192
	v_add_u32_e32 v162, 0x100d0, v251
	s_waitcnt vmcnt(0)
	v_mul_f32_e32 v246, v0, v246
	v_mul_f32_e32 v247, v1, v247
	v_add_f32_e32 v246, v246, v247
	v_add_f32_e32 v246, v4, v246
	v_cmp_lt_i32_e32 vcc, 0, v213
	v_add_u32_e32 v249, 0xfff, v213
	s_nop 0
	v_cndmask_b32_e32 v248, v1, v0, vcc
	v_cmp_eq_u32_e32 vcc, 0, v213
	v_mul_f32_e32 v95, v248, v95
	s_nop 0
	v_cndmask_b32_e32 v95, v95, v246, vcc
	v_cmp_gt_u32_e32 vcc, 0x1fff, v249
	s_nop 1
	v_cndmask_b32_e32 v95, 0, v95, vcc
	v_cmp_lt_i32_e32 vcc, 0, v214
	v_add_u32_e32 v249, 0xfff, v214
	s_nop 0
	v_cndmask_b32_e32 v248, v1, v0, vcc
	v_cmp_eq_u32_e32 vcc, 0, v214
	v_mul_f32_e32 v96, v248, v96
	s_nop 0
	v_cndmask_b32_e32 v96, v96, v246, vcc
	v_cmp_gt_u32_e32 vcc, 0x1fff, v249
	s_nop 1
	v_cndmask_b32_e32 v96, 0, v96, vcc
	v_cmp_lt_i32_e32 vcc, 0, v215
	v_add_u32_e32 v249, 0xfff, v215
	s_nop 0
	v_cndmask_b32_e32 v248, v1, v0, vcc
	v_cmp_eq_u32_e32 vcc, 0, v215
	v_mul_f32_e32 v97, v248, v97
	s_nop 0
	v_cndmask_b32_e32 v97, v97, v246, vcc
	v_cmp_gt_u32_e32 vcc, 0x1fff, v249
	s_nop 1
	v_cndmask_b32_e32 v97, 0, v97, vcc
	v_cmp_lt_i32_e32 vcc, 0, v216
	v_add_u32_e32 v249, 0xfff, v216
	s_nop 0
	v_cndmask_b32_e32 v248, v1, v0, vcc
	v_cmp_eq_u32_e32 vcc, 0, v216
	v_mul_f32_e32 v98, v248, v98
	s_nop 0
	v_cndmask_b32_e32 v98, v98, v246, vcc
	v_cmp_gt_u32_e32 vcc, 0x1fff, v249
	s_nop 1
	v_cndmask_b32_e32 v98, 0, v98, vcc
	v_cmp_lt_i32_e32 vcc, 0, v217
	v_add_u32_e32 v249, 0xfff, v217
	s_nop 0
	v_cndmask_b32_e32 v248, v1, v0, vcc
	v_cmp_eq_u32_e32 vcc, 0, v217
	v_mul_f32_e32 v99, v248, v99
	s_nop 0
	v_cndmask_b32_e32 v99, v99, v246, vcc
	v_cmp_gt_u32_e32 vcc, 0x1fff, v249
	s_nop 1
	v_cndmask_b32_e32 v99, 0, v99, vcc
	v_cmp_lt_i32_e32 vcc, 0, v218
	v_add_u32_e32 v249, 0xfff, v218
	s_nop 0
	v_cndmask_b32_e32 v248, v1, v0, vcc
	v_cmp_eq_u32_e32 vcc, 0, v218
	v_mul_f32_e32 v100, v248, v100
	s_nop 0
	v_cndmask_b32_e32 v100, v100, v246, vcc
	v_cmp_gt_u32_e32 vcc, 0x1fff, v249
	s_nop 1
	v_cndmask_b32_e32 v100, 0, v100, vcc
	v_cmp_lt_i32_e32 vcc, 0, v219
	v_add_u32_e32 v249, 0xfff, v219
	s_nop 0
	v_cndmask_b32_e32 v248, v1, v0, vcc
	v_cmp_eq_u32_e32 vcc, 0, v219
	v_mul_f32_e32 v101, v248, v101
	s_nop 0
	v_cndmask_b32_e32 v101, v101, v246, vcc
	v_cmp_gt_u32_e32 vcc, 0x1fff, v249
	s_nop 1
	v_cndmask_b32_e32 v101, 0, v101, vcc
	v_cmp_lt_i32_e32 vcc, 0, v220
	v_add_u32_e32 v249, 0xfff, v220
	s_nop 0
	v_cndmask_b32_e32 v248, v1, v0, vcc
	v_cmp_eq_u32_e32 vcc, 0, v220
	v_mul_f32_e32 v102, v248, v102
	s_nop 0
	v_cndmask_b32_e32 v102, v102, v246, vcc
	v_cmp_gt_u32_e32 vcc, 0x1fff, v249
	s_nop 1
	v_cndmask_b32_e32 v102, 0, v102, vcc
	v_cmp_lt_i32_e32 vcc, 0, v221
	v_add_u32_e32 v249, 0xfff, v221
	s_nop 0
	v_cndmask_b32_e32 v248, v1, v0, vcc
	v_cmp_eq_u32_e32 vcc, 0, v221
	v_mul_f32_e32 v103, v248, v103
	s_nop 0
	v_cndmask_b32_e32 v103, v103, v246, vcc
	v_cmp_gt_u32_e32 vcc, 0x1fff, v249
	s_nop 1
	v_cndmask_b32_e32 v103, 0, v103, vcc
	v_cmp_lt_i32_e32 vcc, 0, v222
	v_add_u32_e32 v249, 0xfff, v222
	s_nop 0
	v_cndmask_b32_e32 v248, v1, v0, vcc
	v_cmp_eq_u32_e32 vcc, 0, v222
	v_mul_f32_e32 v104, v248, v104
	s_nop 0
	v_cndmask_b32_e32 v104, v104, v246, vcc
	v_cmp_gt_u32_e32 vcc, 0x1fff, v249
	s_nop 1
	v_cndmask_b32_e32 v104, 0, v104, vcc
	v_cmp_lt_i32_e32 vcc, 0, v223
	v_add_u32_e32 v249, 0xfff, v223
	s_nop 0
	v_cndmask_b32_e32 v248, v1, v0, vcc
	v_cmp_eq_u32_e32 vcc, 0, v223
	v_mul_f32_e32 v105, v248, v105
	s_nop 0
	v_cndmask_b32_e32 v105, v105, v246, vcc
	v_cmp_gt_u32_e32 vcc, 0x1fff, v249
	s_nop 1
	v_cndmask_b32_e32 v105, 0, v105, vcc
	v_cmp_lt_i32_e32 vcc, 0, v224
	v_add_u32_e32 v249, 0xfff, v224
	s_nop 0
	v_cndmask_b32_e32 v248, v1, v0, vcc
	v_cmp_eq_u32_e32 vcc, 0, v224
	v_mul_f32_e32 v106, v248, v106
	s_nop 0
	v_cndmask_b32_e32 v106, v106, v246, vcc
	v_cmp_gt_u32_e32 vcc, 0x1fff, v249
	s_nop 1
	v_cndmask_b32_e32 v106, 0, v106, vcc
	v_cmp_lt_i32_e32 vcc, 0, v225
	v_add_u32_e32 v249, 0xfff, v225
	s_nop 0
	v_cndmask_b32_e32 v248, v1, v0, vcc
	v_cmp_eq_u32_e32 vcc, 0, v225
	v_mul_f32_e32 v107, v248, v107
	s_nop 0
	v_cndmask_b32_e32 v107, v107, v246, vcc
	v_cmp_gt_u32_e32 vcc, 0x1fff, v249
	s_nop 1
	v_cndmask_b32_e32 v107, 0, v107, vcc
	v_cmp_lt_i32_e32 vcc, 0, v226
	v_add_u32_e32 v249, 0xfff, v226
	s_nop 0
	v_cndmask_b32_e32 v248, v1, v0, vcc
	v_cmp_eq_u32_e32 vcc, 0, v226
	v_mul_f32_e32 v108, v248, v108
	s_nop 0
	v_cndmask_b32_e32 v108, v108, v246, vcc
	v_cmp_gt_u32_e32 vcc, 0x1fff, v249
	s_nop 1
	v_cndmask_b32_e32 v108, 0, v108, vcc
	v_cmp_lt_i32_e32 vcc, 0, v227
	v_add_u32_e32 v249, 0xfff, v227
	s_nop 0
	v_cndmask_b32_e32 v248, v1, v0, vcc
	v_cmp_eq_u32_e32 vcc, 0, v227
	v_mul_f32_e32 v109, v248, v109
	s_nop 0
	v_cndmask_b32_e32 v109, v109, v246, vcc
	v_cmp_gt_u32_e32 vcc, 0x1fff, v249
	s_nop 1
	v_cndmask_b32_e32 v109, 0, v109, vcc
	v_cmp_lt_i32_e32 vcc, 0, v228
	v_add_u32_e32 v249, 0xfff, v228
	s_nop 0
	v_cndmask_b32_e32 v248, v1, v0, vcc
	v_cmp_eq_u32_e32 vcc, 0, v228
	v_mul_f32_e32 v110, v248, v110
	s_nop 0
	v_cndmask_b32_e32 v110, v110, v246, vcc
	v_cmp_gt_u32_e32 vcc, 0x1fff, v249
	s_nop 1
	v_cndmask_b32_e32 v110, 0, v110, vcc
	v_cmp_lt_i32_e32 vcc, 0, v229
	v_add_u32_e32 v249, 0xfff, v229
	s_nop 0
	v_cndmask_b32_e32 v248, v1, v0, vcc
	v_cmp_eq_u32_e32 vcc, 0, v229
	v_mul_f32_e32 v111, v248, v111
	s_nop 0
	v_cndmask_b32_e32 v111, v111, v246, vcc
	v_cmp_gt_u32_e32 vcc, 0x1fff, v249
	s_nop 1
	v_cndmask_b32_e32 v111, 0, v111, vcc
	v_cmp_lt_i32_e32 vcc, 0, v230
	v_add_u32_e32 v249, 0xfff, v230
	s_nop 0
	v_cndmask_b32_e32 v248, v1, v0, vcc
	v_cmp_eq_u32_e32 vcc, 0, v230
	v_mul_f32_e32 v122, v248, v122
	s_nop 0
	v_cndmask_b32_e32 v122, v122, v246, vcc
	v_cmp_gt_u32_e32 vcc, 0x1fff, v249
	s_nop 1
	v_cndmask_b32_e32 v122, 0, v122, vcc
	v_cmp_lt_i32_e32 vcc, 0, v231
	v_add_u32_e32 v249, 0xfff, v231
	s_nop 0
	v_cndmask_b32_e32 v248, v1, v0, vcc
	v_cmp_eq_u32_e32 vcc, 0, v231
	v_mul_f32_e32 v123, v248, v123
	s_nop 0
	v_cndmask_b32_e32 v123, v123, v246, vcc
	v_cmp_gt_u32_e32 vcc, 0x1fff, v249
	s_nop 1
	v_cndmask_b32_e32 v123, 0, v123, vcc
	v_cmp_lt_i32_e32 vcc, 0, v232
	v_add_u32_e32 v249, 0xfff, v232
	s_nop 0
	v_cndmask_b32_e32 v248, v1, v0, vcc
	v_cmp_eq_u32_e32 vcc, 0, v232
	v_mul_f32_e32 v124, v248, v124
	s_nop 0
	v_cndmask_b32_e32 v124, v124, v246, vcc
	v_cmp_gt_u32_e32 vcc, 0x1fff, v249
	s_nop 1
	v_cndmask_b32_e32 v124, 0, v124, vcc
	v_cmp_lt_i32_e32 vcc, 0, v233
	v_add_u32_e32 v249, 0xfff, v233
	s_nop 0
	v_cndmask_b32_e32 v248, v1, v0, vcc
	v_cmp_eq_u32_e32 vcc, 0, v233
	v_mul_f32_e32 v125, v248, v125
	s_nop 0
	v_cndmask_b32_e32 v125, v125, v246, vcc
	v_cmp_gt_u32_e32 vcc, 0x1fff, v249
	s_nop 1
	v_cndmask_b32_e32 v125, 0, v125, vcc
	v_cmp_lt_i32_e32 vcc, 0, v234
	v_add_u32_e32 v249, 0xfff, v234
	s_nop 0
	v_cndmask_b32_e32 v248, v1, v0, vcc
	v_cmp_eq_u32_e32 vcc, 0, v234
	v_mul_f32_e32 v126, v248, v126
	s_nop 0
	v_cndmask_b32_e32 v126, v126, v246, vcc
	v_cmp_gt_u32_e32 vcc, 0x1fff, v249
	s_nop 1
	v_cndmask_b32_e32 v126, 0, v126, vcc
	v_cmp_lt_i32_e32 vcc, 0, v235
	v_add_u32_e32 v249, 0xfff, v235
	s_nop 0
	v_cndmask_b32_e32 v248, v1, v0, vcc
	v_cmp_eq_u32_e32 vcc, 0, v235
	v_mul_f32_e32 v127, v248, v127
	s_nop 0
	v_cndmask_b32_e32 v127, v127, v246, vcc
	v_cmp_gt_u32_e32 vcc, 0x1fff, v249
	s_nop 1
	v_cndmask_b32_e32 v127, 0, v127, vcc
	v_cvt_pk_bf16_f32 v142, v95, v96
	v_cvt_pk_bf16_f32 v143, v97, v98
	v_cvt_pk_bf16_f32 v144, v99, v100
	v_cvt_pk_bf16_f32 v145, v101, v102
	v_cvt_pk_bf16_f32 v146, v103, v104
	v_cvt_pk_bf16_f32 v147, v105, v106
	v_cvt_pk_bf16_f32 v148, v107, v108
	v_cvt_pk_bf16_f32 v149, v109, v110
	v_cvt_pk_bf16_f32 v150, v111, v122
	v_cvt_pk_bf16_f32 v151, v123, v124
	v_cvt_pk_bf16_f32 v152, v97, v98
	v_cvt_pk_bf16_f32 v153, v99, v100
	v_cvt_pk_bf16_f32 v154, v101, v102
	v_cvt_pk_bf16_f32 v155, v103, v104
	v_cvt_pk_bf16_f32 v156, v105, v106
	v_cvt_pk_bf16_f32 v157, v107, v108
	v_cvt_pk_bf16_f32 v158, v109, v110
	v_cvt_pk_bf16_f32 v159, v111, v122
	v_cvt_pk_bf16_f32 v160, v123, v124
	v_cvt_pk_bf16_f32 v161, v125, v126
	v_cvt_pk_bf16_f32 v236, v96, v97
	v_cvt_pk_bf16_f32 v237, v98, v99
	v_cvt_pk_bf16_f32 v238, v100, v101
	v_cvt_pk_bf16_f32 v239, v102, v103
	v_cvt_pk_bf16_f32 v240, v104, v105
	v_cvt_pk_bf16_f32 v241, v106, v107
	v_cvt_pk_bf16_f32 v242, v108, v109
	v_cvt_pk_bf16_f32 v243, v110, v111
	v_cvt_pk_bf16_f32 v244, v122, v123
	v_cvt_pk_bf16_f32 v245, v124, v125
	v_cvt_pk_bf16_f32 v170, v98, v99
	v_cvt_pk_bf16_f32 v171, v100, v101
	v_cvt_pk_bf16_f32 v172, v102, v103
	v_cvt_pk_bf16_f32 v173, v104, v105
	v_cvt_pk_bf16_f32 v174, v106, v107
	v_cvt_pk_bf16_f32 v175, v108, v109
	v_cvt_pk_bf16_f32 v176, v110, v111
	v_cvt_pk_bf16_f32 v177, v122, v123
	v_cvt_pk_bf16_f32 v178, v124, v125
	v_cvt_pk_bf16_f32 v179, v126, v127
	ds_write_b128 v251, v[142:145] offset:0
	ds_write_b128 v251, v[146:149] offset:16
	ds_write_b128 v251, v[236:239] offset:16400
	ds_write_b128 v251, v[240:243] offset:16416
	ds_write_b128 v251, v[152:155] offset:32848
	ds_write_b128 v251, v[156:159] offset:32864
	ds_write_b128 v251, v[170:173] offset:49296
	ds_write_b128 v251, v[174:177] offset:49312
	ds_write_b128 v162, v[144:147] offset:0
	ds_write_b128 v162, v[148:151] offset:16
	ds_write_b128 v162, v[238:241] offset:16512
	ds_write_b128 v162, v[242:245] offset:16528
	ds_write_b128 v162, v[154:157] offset:32960
	ds_write_b128 v162, v[158:161] offset:32976
	ds_write_b128 v162, v[172:175] offset:49408
	ds_write_b128 v162, v[176:179] offset:49424
	s_andn2_b64 vcc, exec, s[88:89]
	s_cbranch_vccnz .LBB0_721
	global_load_dwordx4 v[0:3], v[56:57], off
	v_add_u32_e32 v4, v17, v67
	s_waitcnt vmcnt(0)
	ds_write_b128 v4, v[0:3]
	global_load_dwordx4 v[0:3], v[58:59], off
	v_add_u32_e32 v4, v17, v66
	s_waitcnt vmcnt(0)
	ds_write_b128 v4, v[0:3]
.LBB0_721:
	v_mov_b32_e32 v0, 0
	s_xor_b64 s[12:13], s[88:89], -1
	s_movk_i32 s0, 0x3f80
	v_mov_b32_e32 v61, v78
	v_mov_b32_e32 v1, v0
	v_mov_b32_e32 v2, v0
	v_mov_b32_e32 v3, v0
	v_mov_b32_e32 v4, v0
	v_mov_b32_e32 v5, v0
	v_mov_b32_e32 v6, v0
	v_mov_b32_e32 v7, v0
	v_mov_b32_e32 v8, v0
	v_mov_b32_e32 v9, v0
	v_mov_b32_e32 v10, v0
	v_mov_b32_e32 v11, v0
	v_mov_b32_e32 v12, v0
	v_mov_b32_e32 v13, v0
	v_mov_b32_e32 v14, v0
	v_mov_b32_e32 v15, v0
	v_mov_b32_e32 v214, 0x24b00
	v_and_b32_e32 v162, 7, v192
	v_lshl_add_u32 v162, v162, 4, v214
	ds_write_b128 v162, v[0:3]
	s_waitcnt lgkmcnt(0)
	s_barrier
